# non-halo group seams signal through per-workgroup flag words (plain store, sc1 poll of the group's 32 flags) instead of polling the atomic counter
# speedup vs baseline: 1.0048x; 1.0026x over previous
.Llb_have:
	global_atomic_add v2, v1, s[10:11]
	v_readlane_b32 s17, v252, 0
	s_nop 0
	s_lshr_b32 s16, s17, 3
	s_lshl_b32 s16, s16, 2
	s_lshl_b32 s17, s8, 7
	s_add_i32 s17, s17, 0x500
	s_add_i32 s16, s16, s17
	v_mov_b32_e32 v2, s16
	s_add_i32 s15, s6, 1
	v_mov_b32_e32 v3, s15
	s_nop 0
	global_store_dword v2, v3, s[10:11]
	s_mov_b64 exec, 0xffffffff
	v_mbcnt_lo_u32_b32 v2, -1, 0
	v_lshl_add_u32 v2, v2, 2, s17
	s_mov_b32 s12, 0
.Llf_poll:
	global_load_dword v0, v2, s[10:11] sc1
	s_waitcnt vmcnt(0)
	v_cmp_le_u32_e32 vcc, s15, v0
	s_nop 1
	s_cmp_eq_u32 vcc_lo, -1
	s_cbranch_scc1 .Llb_done
	s_sleep 1
	s_add_i32 s12, s12, 1
	s_cmp_lt_u32 s12, 0x2000
	s_cbranch_scc1 .Llf_poll
	s_branch .Llb_done
